# selection loop software-pipelined: PV MFMAs of pair p-1 issued under the max tree and exp2 work of pair p; V loads for pair p inside that PV
# baseline (speedup 1.0000x reference)
; __device__ __forceinline__ float bf2f(bf16_t b) { return __uint_as_float(((unsigned)b) << 16); }
; __device__ __forceinline__ void nsa_unit(const Params& p, int bg, int jq, LAS unsigned char* lds, int wave, int lane, bool build_lut) {
;     ...
;             long q8[2];
;             bf16x8 qv2[2];
;             {
;                 const bf16_t* qp = qb + ((size_t)b * S + tqg) * 512 + (g * 4 + r16) * 64 + 8 * fq;
;                 qv2[0] = *(const bf16x8*)(qp); qv2[1] = *(const bf16x8*)(qp + 32);
;             }
;             float m = -1e30f;
;             f32x4 lacc = (f32x4){0.f, 0.f, 0.f, 0.f};
;             const long ones8 = 0x3838383838383838L;
;             f32x4 o[4];
; #pragma unroll
;             for (int dt = 0; dt < 4; ++dt) o[dt] = (f32x4){0.f, 0.f, 0.f, 0.f};
;             const int npair = (cnt + 1) >> 1;
;             if (lane == 0 && (cnt & 1)) list[lbase + cnt] = 0;
;             asm volatile("s_waitcnt lgkmcnt(0)" ::: "memory");
;             __builtin_amdgcn_wave_barrier();
;             long k8[2][8], v8[2][8];
;             int n0 = __builtin_amdgcn_readfirstlane(list[lbase]), n1 = __builtin_amdgcn_readfirstlane(list[lbase + 1]);
; #pragma unroll
;             for (int i = 0; i < 4; ++i) { const l64x2 t0 = *(const l64x2*)(ks8 + (size_t)n0 * 4096 + i * 1024 + lane * 16), t1 = *(const l64x2*)(ks8 + (size_t)n1 * 4096 + i * 1024 + lane * 16);
;                 k8[0][2 * i] = t0[0]; k8[0][2 * i + 1] = t0[1]; k8[1][2 * i] = t1[0]; k8[1][2 * i + 1] = t1[1]; }
; #pragma unroll
;             for (int ks = 0; ks < 2; ++ks) {
;                 float f[8];
; #pragma unroll
;                 for (int e = 0; e < 8; ++e) f[e] = bf2f((bf16_t)qv2[ks][e]) * 4.0f;
;                 q8[ks] = pack_fp8x8(f[0], f[1], f[2], f[3], f[4], f[5], f[6], f[7]);
;             }
;             for (int it = 0; it < npair; ++it) {
.LBB0_1198:
	s_or_b64 exec, exec, s[4:5]
	s_lshl_b32 s4, s8, 2
	s_add_i32 s4, s34, s4
	v_mov_b32_e32 v1, s4
	s_waitcnt lgkmcnt(0)
	ds_read_b64 v[4:5], v1 offset:10560
	s_cmp_lg_u32 s38, 0
	v_or_b32_e32 v165, s7, v160
	s_waitcnt lgkmcnt(0)
	v_readfirstlane_b32 s22, v4
	v_readfirstlane_b32 s8, v5
	s_cbranch_scc0 .LBB0_1279
	s_ashr_i32 s9, s8, 31
	s_lshl_b64 s[4:5], s[8:9], 12
	s_ashr_i32 s23, s22, 31
	v_lshl_add_u64 v[4:5], v[148:149], 0, s[4:5]
	s_lshl_b64 s[4:5], s[22:23], 12
	v_lshl_add_u64 v[16:17], v[148:149], 0, s[4:5]
	global_load_dwordx4 v[32:35], v[4:5], off offset:3072
	global_load_dwordx4 v[8:11], v[4:5], off offset:2048
	global_load_dwordx4 v[36:39], v[16:17], off offset:3072
	global_load_dwordx4 v[20:23], v[16:17], off offset:2048
	global_load_dwordx4 v[12:15], v[4:5], off offset:1024
	s_nop 0
	global_load_dwordx4 v[4:7], v[4:5], off
	s_nop 0
	global_load_dwordx4 v[28:31], v[16:17], off offset:1024
	s_nop 0
	global_load_dwordx4 v[16:19], v[16:17], off
	s_waitcnt vmcnt(9)
	v_lshlrev_b32_e32 v1, 16, v40
	v_and_b32_e32 v3, 0xffff0000, v40
	v_lshlrev_b32_e32 v44, 16, v42
	v_and_b32_e32 v42, 0xffff0000, v42
	v_mul_f32_e32 v1, 4.0, v1
	v_mul_f32_e32 v3, 4.0, v3
	v_mul_f32_e32 v44, 4.0, v44
	v_mul_f32_e32 v42, 4.0, v42
	v_mov_b32_e32 v152, 0
	v_mov_b32_e32 v153, 0
	v_cvt_pk_fp8_f32 v152, v1, v3
	v_cvt_pk_fp8_f32 v153, v44, v42
	v_lshlrev_b32_e32 v40, 16, v41
	v_and_b32_e32 v41, 0xffff0000, v41
	v_lshlrev_b32_e32 v45, 16, v43
	v_and_b32_e32 v1, 0xffff0000, v43
	v_mul_f32_e32 v40, 4.0, v40
	v_mul_f32_e32 v41, 4.0, v41
	v_mul_f32_e32 v45, 4.0, v45
	v_mul_f32_e32 v1, 4.0, v1
	v_cvt_pk_fp8_f32 v152, v40, v41 op_sel:[0,0,1]
	v_cvt_pk_fp8_f32 v153, v45, v1 op_sel:[0,0,1]
	s_waitcnt vmcnt(8)
	v_lshlrev_b32_e32 v1, 16, v24
	v_and_b32_e32 v3, 0xffff0000, v24
	v_lshlrev_b32_e32 v40, 16, v26
	v_and_b32_e32 v26, 0xffff0000, v26
	v_mul_f32_e32 v1, 4.0, v1
	v_mul_f32_e32 v3, 4.0, v3
	v_mul_f32_e32 v40, 4.0, v40
	v_mul_f32_e32 v26, 4.0, v26
	v_mov_b32_e32 v154, 0
	v_mov_b32_e32 v155, 0
	v_cvt_pk_fp8_f32 v154, v1, v3
	v_cvt_pk_fp8_f32 v155, v40, v26
	v_lshlrev_b32_e32 v24, 16, v25
	v_and_b32_e32 v25, 0xffff0000, v25
	v_lshlrev_b32_e32 v41, 16, v27
	v_and_b32_e32 v1, 0xffff0000, v27
	v_mul_f32_e32 v24, 4.0, v24
	v_mul_f32_e32 v25, 4.0, v25
	v_mul_f32_e32 v41, 4.0, v41
	v_mul_f32_e32 v1, 4.0, v1
	v_cvt_pk_fp8_f32 v154, v24, v25 op_sel:[0,0,1]
	v_cvt_pk_fp8_f32 v155, v41, v1 op_sel:[0,0,1]
	s_add_i32 s4, s38, 1
	v_sub_u32_e32 v168, v2, v163
	v_add_u32_e32 v169, v2, v164
	v_mov_b32_e32 v2, v0
	v_mov_b32_e32 v3, v0
	s_lshr_b32 s41, s4, 1
	v_or_b32_e32 v166, s7, v160
	s_lshl_b32 s4, s6, 8
	v_mov_b32_e32 v1, v0
	v_mov_b64_e32 v[26:27], v[2:3]
	v_mov_b64_e32 v[42:43], v[2:3]
	v_mov_b64_e32 v[46:47], v[2:3]
	v_mov_b64_e32 v[50:51], v[2:3]
	v_mov_b64_e32 v[54:55], v[2:3]
	s_mov_b32 s40, 1
	v_lshl_add_u32 v167, v166, 5, s34
	s_max_u32 s42, s41, 1
	v_add_u32_e32 v170, -2, v168
	v_add_u32_e32 v171, -3, v168
	v_add_u32_e32 v172, -16, v168
	v_subrev_u32_e32 v173, 17, v168
	v_subrev_u32_e32 v174, 18, v168
	v_subrev_u32_e32 v175, 19, v168
	v_subrev_u32_e32 v176, 32, v168
	v_subrev_u32_e32 v185, 33, v168
	v_subrev_u32_e32 v186, 34, v168
	v_subrev_u32_e32 v187, 35, v168
	v_subrev_u32_e32 v188, 48, v168
	v_subrev_u32_e32 v189, 49, v168
	v_subrev_u32_e32 v190, 50, v168
	v_subrev_u32_e32 v191, 51, v168
	s_add_i32 s43, s37, s4
	v_mov_b32_e32 v157, 0xf149f2ca
	v_mov_b32_e32 v242, 0x38383838
	v_mov_b32_e32 v243, 0x38383838
	s_mov_b32 s44, 0
	v_mov_b64_e32 v[24:25], v[0:1]
	v_mov_b64_e32 v[40:41], v[0:1]
	v_mov_b64_e32 v[44:45], v[0:1]
	v_mov_b64_e32 v[48:49], v[0:1]
	v_mov_b64_e32 v[52:53], v[0:1]
	s_waitcnt vmcnt(0)
.LBB0_1200:
	v_mov_b32_e32 v238, s43
	ds_read_b64 v[238:239], v238
	s_ashr_i32 s6, s22, 5
	v_lshl_add_u32 v1, s6, 2, v167
	ds_read_b32 v1, v1 offset:8192
	s_ashr_i32 s6, s8, 5
	v_lshl_add_u32 v2, s6, 2, v167
	ds_read_b32 v240, v2 offset:8192
	s_cmp_lt_u32 s40, s38
	s_cselect_b64 s[4:5], -1, 0
	s_waitcnt lgkmcnt(0)
	v_lshrrev_b32_e32 v2, s8, v240
	v_and_b32_e32 v2, 1, v2
	v_cmp_eq_u32_e32 vcc, 1, v2
	s_and_b64 s[20:21], vcc, s[4:5]

; __device__ __forceinline__ void nsa_unit(const Params& p, int bg, int jq, LAS unsigned char* lds, int wave, int lane, bool build_lut) {
;     ...
;                 for (int u = 0; u < 2; ++u)
; #pragma unroll
;                     for (int i = 0; i < 4; ++i) { const l64x2 t = *(const l64x2*)(vs8 + (size_t)nb[u] * 4096 + i * 1024 + lane * 16); v8[u][2 * i] = t[0]; v8[u][2 * i + 1] = t[1]; }
;     ...
; #pragma unroll
;                 for (int u = 0; u < 2; ++u) {
;                     const long pb0 = pack_fp8x8(sc[u][0][0], sc[u][0][1], sc[u][0][2], sc[u][0][3], sc[u][1][0], sc[u][1][1], sc[u][1][2], sc[u][1][3]);
;                     const long pb1 = pack_fp8x8(sc[u][2][0], sc[u][2][1], sc[u][2][2], sc[u][2][3], sc[u][3][0], sc[u][3][1], sc[u][3][2], sc[u][3][3]);
; #pragma unroll
;                     for (int dt = 0; dt < 4; ++dt) {
;                         o[dt] = __builtin_amdgcn_mfma_f32_16x16x32_fp8_fp8(v8[u][2 * dt], pb0, o[dt], 0, 0, 0);
;                         o[dt] = __builtin_amdgcn_mfma_f32_16x16x32_fp8_fp8(v8[u][2 * dt + 1], pb1, o[dt], 0, 0, 0);
;                     }
;                     lacc = __builtin_amdgcn_mfma_f32_16x16x32_fp8_fp8(ones8, pb0, lacc, 0, 0, 0);
;                     lacc = __builtin_amdgcn_mfma_f32_16x16x32_fp8_fp8(ones8, pb1, lacc, 0, 0, 0);
;                 }
.LBB0_1204:
	s_andn2_b64 vcc, exec, s[24:25]
	s_mov_b64 s[24:25], -1
	s_cbranch_vccnz .Lsel_fast
	s_cmp_eq_u32 s44, 1
	s_cbranch_scc1 .Lslow_first
	s_cmp_ge_u32 s44, s41
	s_cbranch_scc1 .Lslow_pv_last
	s_ashr_i32 s23, s22, 31
	s_lshl_b64 s[46:47], s[22:23], 12
	v_lshl_add_u64 v[234:235], v[150:151], 0, s[46:47]
	s_ashr_i32 s9, s8, 31
	s_lshl_b64 s[46:47], s[8:9], 12
	v_lshl_add_u64 v[236:237], v[150:151], 0, s[46:47]
	s_waitcnt vmcnt(15)
	v_mfma_f32_16x16x32_fp8_fp8 v[48:51], v[84:85], v[244:245], v[48:51]
	v_mfma_f32_16x16x32_fp8_fp8 v[52:55], v[242:243], v[244:245], v[52:55]
	s_waitcnt vmcnt(14)
	v_mfma_f32_16x16x32_fp8_fp8 v[44:47], v[80:81], v[244:245], v[44:47]
	s_waitcnt vmcnt(13)
	v_mfma_f32_16x16x32_fp8_fp8 v[40:43], v[76:77], v[244:245], v[40:43]
	s_waitcnt vmcnt(12)
	v_mfma_f32_16x16x32_fp8_fp8 v[24:27], v[72:73], v[244:245], v[24:27]
	v_mfma_f32_16x16x32_fp8_fp8 v[48:51], v[86:87], v[246:247], v[48:51]
	global_load_dwordx4 v[84:87], v[234:235], off
	v_mfma_f32_16x16x32_fp8_fp8 v[44:47], v[82:83], v[246:247], v[44:47]
	global_load_dwordx4 v[80:83], v[234:235], off offset:1024
	v_mfma_f32_16x16x32_fp8_fp8 v[40:43], v[78:79], v[246:247], v[40:43]
	global_load_dwordx4 v[76:79], v[234:235], off offset:2048
	v_mfma_f32_16x16x32_fp8_fp8 v[24:27], v[74:75], v[246:247], v[24:27]
	global_load_dwordx4 v[72:75], v[234:235], off offset:3072
	v_mfma_f32_16x16x32_fp8_fp8 v[52:55], v[242:243], v[246:247], v[52:55]
	s_waitcnt vmcnt(15)
	v_mfma_f32_16x16x32_fp8_fp8 v[48:51], v[68:69], v[248:249], v[48:51]
	v_mfma_f32_16x16x32_fp8_fp8 v[52:55], v[242:243], v[248:249], v[52:55]
	s_waitcnt vmcnt(14)
	v_mfma_f32_16x16x32_fp8_fp8 v[44:47], v[64:65], v[248:249], v[44:47]
	s_waitcnt vmcnt(13)
	v_mfma_f32_16x16x32_fp8_fp8 v[40:43], v[60:61], v[248:249], v[40:43]
	s_waitcnt vmcnt(12)
	v_mfma_f32_16x16x32_fp8_fp8 v[24:27], v[56:57], v[248:249], v[24:27]
	v_mfma_f32_16x16x32_fp8_fp8 v[48:51], v[70:71], v[250:251], v[48:51]
	global_load_dwordx4 v[68:71], v[236:237], off
	v_mfma_f32_16x16x32_fp8_fp8 v[44:47], v[66:67], v[250:251], v[44:47]
	global_load_dwordx4 v[64:67], v[236:237], off offset:1024
	v_mfma_f32_16x16x32_fp8_fp8 v[40:43], v[62:63], v[250:251], v[40:43]
	global_load_dwordx4 v[60:63], v[236:237], off offset:2048
	v_mfma_f32_16x16x32_fp8_fp8 v[24:27], v[58:59], v[250:251], v[24:27]
	global_load_dwordx4 v[56:59], v[236:237], off offset:3072
	v_mfma_f32_16x16x32_fp8_fp8 v[52:55], v[242:243], v[250:251], v[52:55]
	s_branch .Lslow_chain
.Lslow_pv_last:
	s_ashr_i32 s23, s22, 31
	s_lshl_b64 s[46:47], s[22:23], 12
	v_lshl_add_u64 v[234:235], v[150:151], 0, s[46:47]
	s_ashr_i32 s9, s8, 31
	s_lshl_b64 s[46:47], s[8:9], 12
	v_lshl_add_u64 v[236:237], v[150:151], 0, s[46:47]
	s_waitcnt vmcnt(7)
	v_mfma_f32_16x16x32_fp8_fp8 v[48:51], v[84:85], v[244:245], v[48:51]
	v_mfma_f32_16x16x32_fp8_fp8 v[52:55], v[242:243], v[244:245], v[52:55]
	s_waitcnt vmcnt(6)
	v_mfma_f32_16x16x32_fp8_fp8 v[44:47], v[80:81], v[244:245], v[44:47]
	s_waitcnt vmcnt(5)
	v_mfma_f32_16x16x32_fp8_fp8 v[40:43], v[76:77], v[244:245], v[40:43]
	s_waitcnt vmcnt(4)
	v_mfma_f32_16x16x32_fp8_fp8 v[24:27], v[72:73], v[244:245], v[24:27]
	v_mfma_f32_16x16x32_fp8_fp8 v[48:51], v[86:87], v[246:247], v[48:51]
	global_load_dwordx4 v[84:87], v[234:235], off
	v_mfma_f32_16x16x32_fp8_fp8 v[44:47], v[82:83], v[246:247], v[44:47]
	global_load_dwordx4 v[80:83], v[234:235], off offset:1024
	v_mfma_f32_16x16x32_fp8_fp8 v[40:43], v[78:79], v[246:247], v[40:43]
	global_load_dwordx4 v[76:79], v[234:235], off offset:2048
	v_mfma_f32_16x16x32_fp8_fp8 v[24:27], v[74:75], v[246:247], v[24:27]
	global_load_dwordx4 v[72:75], v[234:235], off offset:3072
	v_mfma_f32_16x16x32_fp8_fp8 v[52:55], v[242:243], v[246:247], v[52:55]
	s_waitcnt vmcnt(7)
	v_mfma_f32_16x16x32_fp8_fp8 v[48:51], v[68:69], v[248:249], v[48:51]
	v_mfma_f32_16x16x32_fp8_fp8 v[52:55], v[242:243], v[248:249], v[52:55]
	s_waitcnt vmcnt(6)
	v_mfma_f32_16x16x32_fp8_fp8 v[44:47], v[64:65], v[248:249], v[44:47]
	s_waitcnt vmcnt(5)
	v_mfma_f32_16x16x32_fp8_fp8 v[40:43], v[60:61], v[248:249], v[40:43]
	s_waitcnt vmcnt(4)
	v_mfma_f32_16x16x32_fp8_fp8 v[24:27], v[56:57], v[248:249], v[24:27]
	v_mfma_f32_16x16x32_fp8_fp8 v[48:51], v[70:71], v[250:251], v[48:51]
	global_load_dwordx4 v[68:71], v[236:237], off
	v_mfma_f32_16x16x32_fp8_fp8 v[44:47], v[66:67], v[250:251], v[44:47]
	global_load_dwordx4 v[64:67], v[236:237], off offset:1024
	v_mfma_f32_16x16x32_fp8_fp8 v[40:43], v[62:63], v[250:251], v[40:43]
	global_load_dwordx4 v[60:63], v[236:237], off offset:2048
	v_mfma_f32_16x16x32_fp8_fp8 v[24:27], v[58:59], v[250:251], v[24:27]
	global_load_dwordx4 v[56:59], v[236:237], off offset:3072
	v_mfma_f32_16x16x32_fp8_fp8 v[52:55], v[242:243], v[250:251], v[52:55]
	s_branch .Lslow_chain
.Lslow_first:
	s_ashr_i32 s23, s22, 31
	s_lshl_b64 s[46:47], s[22:23], 12
	v_lshl_add_u64 v[234:235], v[150:151], 0, s[46:47]
	s_ashr_i32 s9, s8, 31
	s_lshl_b64 s[46:47], s[8:9], 12
	v_lshl_add_u64 v[236:237], v[150:151], 0, s[46:47]
	global_load_dwordx4 v[84:87], v[234:235], off
	global_load_dwordx4 v[80:83], v[234:235], off offset:1024
	global_load_dwordx4 v[76:79], v[234:235], off offset:2048
	global_load_dwordx4 v[72:75], v[234:235], off offset:3072
	global_load_dwordx4 v[68:71], v[236:237], off
	global_load_dwordx4 v[64:67], v[236:237], off offset:1024
	global_load_dwordx4 v[60:63], v[236:237], off offset:2048
	global_load_dwordx4 v[56:59], v[236:237], off offset:3072
; __device__ __forceinline__ float xhalf_max(float x) { auto t = __builtin_amdgcn_permlane32_swap(__float_as_uint(x), __float_as_uint(x), false, false); return fmaxf(__uint_as_float(t[0]), __uint_as_float(t[1])); }
; __device__ __forceinline__ void nsa_unit(const Params& p, int bg, int jq, LAS unsigned char* lds, int wave, int lane, bool build_lut) {
;     ...
;                     float mx = NEG_INF;
; #pragma unroll
;                     for (int u = 0; u < 2; ++u)
; #pragma unroll
;                         for (int kt = 0; kt < 4; ++kt)
; #pragma unroll
;                             for (int e = 0; e < 4; ++e) {
;                                 const int d = tqg - 64 * nb[u] - 16 * kt - 4 * fq - e;
;                                 const bool okk = ok[u] && d >= 0;
;                                 const float v = okk ? (sc[u][kt][e] + lutr16[min(max(d, 0), 128)]) : NEG_INF;
;                                 sc[u][kt][e] = v; mx = fmaxf(mx, v);
;                             }
;                     { auto t1 = __builtin_amdgcn_permlane16_swap(__float_as_uint(mx), __float_as_uint(mx), false, false); mx = fmaxf(__uint_as_float(t1[0]), __uint_as_float(t1[1])); mx = xhalf_max(mx); }
;                     if (__any(mx > m + 2.0f)) {
.Lslow_chain:
	s_lshl_b32 s9, s22, 6
	s_lshl_b32 s8, s8, 6
	v_mov_b32_e32 v240, 0xff800000
	v_mov_b32_e32 v2, 0x7fffffff
	v_mov_b32_e32 v3, s9
	v_cndmask_b32_e64 v232, v2, v3, s[6:7]
	v_mov_b32_e32 v3, s8
	v_cndmask_b32_e64 v233, v2, v3, s[20:21]
	v_add_u32_e32 v1, 0x20f4, v231
	v_subrev_u32_e32 v192, s9, v168
	v_min_u32_e32 v192, 0x83, v192
	v_lshl_add_u32 v192, v192, 2, v1
	ds_read2_b32 v[194:195], v192 offset0:1 offset1:0
	ds_read2_b32 v[192:193], v192 offset0:3 offset1:2
	v_subrev_u32_e32 v196, s9, v172
	v_min_u32_e32 v196, 0x83, v196
	v_lshl_add_u32 v196, v196, 2, v1
	ds_read2_b32 v[198:199], v196 offset0:1 offset1:0
	ds_read2_b32 v[196:197], v196 offset0:3 offset1:2
	v_subrev_u32_e32 v200, s9, v176
	v_min_u32_e32 v200, 0x83, v200
	v_lshl_add_u32 v200, v200, 2, v1
	ds_read2_b32 v[202:203], v200 offset0:1 offset1:0
	ds_read2_b32 v[200:201], v200 offset0:3 offset1:2
	v_subrev_u32_e32 v204, s9, v188
	v_min_u32_e32 v204, 0x83, v204
	v_lshl_add_u32 v204, v204, 2, v1
	ds_read2_b32 v[206:207], v204 offset0:1 offset1:0
	ds_read2_b32 v[204:205], v204 offset0:3 offset1:2
	v_subrev_u32_e32 v208, s8, v168
	v_min_u32_e32 v208, 0x83, v208
	v_lshl_add_u32 v208, v208, 2, v1
	ds_read2_b32 v[210:211], v208 offset0:1 offset1:0
	ds_read2_b32 v[208:209], v208 offset0:3 offset1:2
	v_subrev_u32_e32 v212, s8, v172
	v_min_u32_e32 v212, 0x83, v212
	v_lshl_add_u32 v212, v212, 2, v1
	ds_read2_b32 v[214:215], v212 offset0:1 offset1:0
	ds_read2_b32 v[212:213], v212 offset0:3 offset1:2
	v_subrev_u32_e32 v216, s8, v176
	v_min_u32_e32 v216, 0x83, v216
	v_lshl_add_u32 v216, v216, 2, v1
	ds_read2_b32 v[218:219], v216 offset0:1 offset1:0
	ds_read2_b32 v[216:217], v216 offset0:3 offset1:2
	v_subrev_u32_e32 v124, s8, v188
	v_min_u32_e32 v124, 0x83, v124
	v_lshl_add_u32 v124, v124, 2, v1
	ds_read2_b32 v[126:127], v124 offset0:1 offset1:0
	ds_read2_b32 v[124:125], v124 offset0:3 offset1:2
	s_waitcnt lgkmcnt(14)
	v_cmp_ge_i32_e32 vcc, v168, v232
	v_cmp_ge_i32_e64 s[46:47], v169, v232
	v_add_f32_e32 v116, v116, v192
	v_add_f32_e32 v117, v117, v193
	v_cndmask_b32_e32 v116, v240, v116, vcc
	v_cndmask_b32_e64 v117, v240, v117, s[46:47]
	v_cmp_ge_i32_e32 vcc, v170, v232
	v_cmp_ge_i32_e64 s[46:47], v171, v232
	v_add_f32_e32 v118, v118, v194
	v_add_f32_e32 v119, v119, v195
	v_cndmask_b32_e32 v118, v240, v118, vcc
	v_cndmask_b32_e64 v119, v240, v119, s[46:47]
	s_waitcnt lgkmcnt(12)
	v_cmp_ge_i32_e32 vcc, v172, v232
	v_cmp_ge_i32_e64 s[46:47], v173, v232
	v_add_f32_e32 v108, v108, v196
	v_add_f32_e32 v109, v109, v197
	v_cndmask_b32_e32 v108, v240, v108, vcc
	v_cndmask_b32_e64 v109, v240, v109, s[46:47]
	v_cmp_ge_i32_e32 vcc, v174, v232
	v_cmp_ge_i32_e64 s[46:47], v175, v232
	v_add_f32_e32 v110, v110, v198
	v_add_f32_e32 v111, v111, v199
	v_cndmask_b32_e32 v110, v240, v110, vcc
	v_cndmask_b32_e64 v111, v240, v111, s[46:47]
	s_waitcnt lgkmcnt(10)
	v_cmp_ge_i32_e32 vcc, v176, v232
	v_cmp_ge_i32_e64 s[46:47], v185, v232
	v_add_f32_e32 v96, v96, v200
	v_add_f32_e32 v97, v97, v201
	v_cndmask_b32_e32 v96, v240, v96, vcc
	v_cndmask_b32_e64 v97, v240, v97, s[46:47]
	v_cmp_ge_i32_e32 vcc, v186, v232
	v_cmp_ge_i32_e64 s[46:47], v187, v232
	v_add_f32_e32 v98, v98, v202
	v_add_f32_e32 v99, v99, v203
	v_cndmask_b32_e32 v98, v240, v98, vcc
	v_cndmask_b32_e64 v99, v240, v99, s[46:47]
	s_waitcnt lgkmcnt(8)
	v_cmp_ge_i32_e32 vcc, v188, v232
	v_cmp_ge_i32_e64 s[46:47], v189, v232
	v_add_f32_e32 v100, v100, v204
	v_add_f32_e32 v101, v101, v205
	v_cndmask_b32_e32 v100, v240, v100, vcc
	v_cndmask_b32_e64 v101, v240, v101, s[46:47]
	v_cmp_ge_i32_e32 vcc, v190, v232
	v_cmp_ge_i32_e64 s[46:47], v191, v232
	v_add_f32_e32 v102, v102, v206
	v_add_f32_e32 v103, v103, v207
	v_cndmask_b32_e32 v102, v240, v102, vcc
	v_cndmask_b32_e64 v103, v240, v103, s[46:47]
	s_waitcnt lgkmcnt(6)
	v_cmp_ge_i32_e32 vcc, v168, v233
	v_cmp_ge_i32_e64 s[46:47], v169, v233
	v_add_f32_e32 v112, v112, v208
	v_add_f32_e32 v113, v113, v209
	v_cndmask_b32_e32 v112, v240, v112, vcc
	v_cndmask_b32_e64 v113, v240, v113, s[46:47]
	v_cmp_ge_i32_e32 vcc, v170, v233
	v_cmp_ge_i32_e64 s[46:47], v171, v233
	v_add_f32_e32 v114, v114, v210
	v_add_f32_e32 v115, v115, v211
	v_cndmask_b32_e32 v114, v240, v114, vcc
	v_cndmask_b32_e64 v115, v240, v115, s[46:47]
	s_waitcnt lgkmcnt(4)
	v_cmp_ge_i32_e32 vcc, v172, v233
	v_cmp_ge_i32_e64 s[46:47], v173, v233
	v_add_f32_e32 v104, v104, v212
	v_add_f32_e32 v105, v105, v213
	v_cndmask_b32_e32 v104, v240, v104, vcc
	v_cndmask_b32_e64 v105, v240, v105, s[46:47]
	v_cmp_ge_i32_e32 vcc, v174, v233
	v_cmp_ge_i32_e64 s[46:47], v175, v233
	v_add_f32_e32 v106, v106, v214
	v_add_f32_e32 v107, v107, v215
	v_cndmask_b32_e32 v106, v240, v106, vcc
	v_cndmask_b32_e64 v107, v240, v107, s[46:47]
	s_waitcnt lgkmcnt(2)
	v_cmp_ge_i32_e32 vcc, v176, v233
	v_cmp_ge_i32_e64 s[46:47], v185, v233
	v_add_f32_e32 v92, v92, v216
	v_add_f32_e32 v93, v93, v217
	v_cndmask_b32_e32 v92, v240, v92, vcc
	v_cndmask_b32_e64 v93, v240, v93, s[46:47]
	v_cmp_ge_i32_e32 vcc, v186, v233
	v_cmp_ge_i32_e64 s[46:47], v187, v233
	v_add_f32_e32 v94, v94, v218
	v_add_f32_e32 v95, v95, v219
	v_cndmask_b32_e32 v94, v240, v94, vcc
	v_cndmask_b32_e64 v95, v240, v95, s[46:47]
	s_waitcnt lgkmcnt(0)
	v_cmp_ge_i32_e32 vcc, v188, v233
	v_cmp_ge_i32_e64 s[46:47], v189, v233
	v_add_f32_e32 v88, v88, v124
	v_add_f32_e32 v89, v89, v125
	v_cndmask_b32_e32 v88, v240, v88, vcc
	v_cndmask_b32_e64 v89, v240, v89, s[46:47]
	v_cmp_ge_i32_e32 vcc, v190, v233
	v_cmp_ge_i32_e64 s[46:47], v191, v233
	v_add_f32_e32 v90, v90, v126
	v_add_f32_e32 v91, v91, v127
	v_cndmask_b32_e32 v90, v240, v90, vcc
	v_cndmask_b32_e64 v91, v240, v91, s[46:47]
	v_max3_f32 v1, v116, v117, v118
	v_max3_f32 v2, v119, v108, v109
	v_max3_f32 v3, v110, v111, v100
	v_max3_f32 v120, v101, v102, v103
	v_max3_f32 v121, v112, v113, v114
	v_max3_f32 v122, v115, v104, v105
	v_max3_f32 v123, v106, v107, v96
	v_max3_f32 v1, v1, v97, v98
	v_max3_f32 v2, v2, v99, v92
	v_max3_f32 v3, v3, v93, v94
	v_max3_f32 v120, v120, v95, v88
	v_max3_f32 v121, v121, v89, v90
	v_max3_f32 v122, v122, v91, v123
	v_max3_f32 v1, v1, v2, v3
	v_max3_f32 v120, v120, v121, v122
	v_max_f32_e32 v1, v1, v120
	v_mov_b32_e32 v2, v1
	s_nop 1
	v_permlane16_swap_b32_e32 v1, v2
	v_max_f32_e32 v1, v1, v2
	v_mov_b32_e32 v2, v1
	s_nop 1
	v_permlane32_swap_b32_e32 v1, v2
	v_max_f32_e32 v1, v1, v2
	v_add_f32_e32 v2, 2.0, v157
	v_cmp_gt_f32_e32 vcc, v1, v2
	s_nop 1
	s_cbranch_vccz .Lslow_nors
; __device__ __forceinline__ float fast_exp2(float x) { return __builtin_amdgcn_exp2f(x); }
; __device__ __forceinline__ void nsa_unit(const Params& p, int bg, int jq, LAS unsigned char* lds, int wave, int lane, bool build_lut) {
;     ...
;                         const float mnew = (mx > m + 2.0f) ? mx : m;
;                         const float alpha = fast_exp2(m - mnew);
;                         lacc = lacc * alpha; m = mnew;
; #pragma unroll
;                         for (int dt = 0; dt < 4; ++dt) o[dt] = o[dt] * alpha;
;                     }
	s_nop 0
	v_cndmask_b32_e32 v3, v157, v1, vcc
	v_sub_f32_e32 v2, v157, v3
	v_exp_f32_e32 v2, v2
	v_mov_b32_e32 v157, v3
	s_nop 0
	v_pk_mul_f32 v[50:51], v[50:51], v[2:3] op_sel_hi:[1,0]
	v_pk_mul_f32 v[48:49], v[48:49], v[2:3] op_sel_hi:[1,0]
	v_pk_mul_f32 v[46:47], v[46:47], v[2:3] op_sel_hi:[1,0]
	v_pk_mul_f32 v[44:45], v[44:45], v[2:3] op_sel_hi:[1,0]
	v_pk_mul_f32 v[42:43], v[42:43], v[2:3] op_sel_hi:[1,0]
	v_pk_mul_f32 v[40:41], v[40:41], v[2:3] op_sel_hi:[1,0]
	v_pk_mul_f32 v[26:27], v[26:27], v[2:3] op_sel_hi:[1,0]
	v_pk_mul_f32 v[24:25], v[24:25], v[2:3] op_sel_hi:[1,0]
	v_pk_mul_f32 v[54:55], v[54:55], v[2:3] op_sel_hi:[1,0]
	v_pk_mul_f32 v[52:53], v[52:53], v[2:3] op_sel_hi:[1,0]

; __device__ __forceinline__ void nsa_unit(const Params& p, int bg, int jq, LAS unsigned char* lds, int wave, int lane, bool build_lut) {
;     ...
;                 if (fast) {
;                     float t = NEG_INF;
; #pragma unroll
;                     for (int u = 0; u < 2; ++u) {
;                         float tt = fmaxf(fmaxf(fmaxf(sc[u][0][0], sc[u][0][1]), fmaxf(sc[u][0][2], sc[u][0][3])), fmaxf(fmaxf(sc[u][1][0], sc[u][1][1]), fmaxf(sc[u][1][2], sc[u][1][3])));
;                         tt = fmaxf(tt, fmaxf(fmaxf(fmaxf(sc[u][2][0], sc[u][2][1]), fmaxf(sc[u][2][2], sc[u][2][3])), fmaxf(fmaxf(sc[u][3][0], sc[u][3][1]), fmaxf(sc[u][3][2], sc[u][3][3]))));
;                         t = fmaxf(t, tt);
;                     }
;                     { auto t1 = __builtin_amdgcn_permlane16_swap(__float_as_uint(t), __float_as_uint(t), false, false); t = fmaxf(__uint_as_float(t1[0]), __uint_as_float(t1[1])); t = xhalf_max(t); }
;                     const float mxt = t - 6.0f + mref;
;                     const bool need = fresh ? (t > NEG_INF) : (mxt > m + 2.0f);
;                     if (__any(need)) {
;                         const float mnew = need ? mxt : m;
;                         const float delta = need ? (mnew - mref) : 0.f;
;                         const float alpha = (need && !fresh) ? fast_exp2(m - mnew) : 1.0f;
;                         lacc = lacc * alpha; m = mnew;
; #pragma unroll
;                         for (int dt = 0; dt < 4; ++dt) o[dt] = o[dt] * alpha;
; #pragma unroll
;                         for (int u = 0; u < 2; ++u)
; #pragma unroll
;                             for (int kt = 0; kt < 4; ++kt) sc[u][kt] = sc[u][kt] - delta;
;                     }
; #pragma unroll
;                     for (int u = 0; u < 2; ++u)
; #pragma unroll
;                         for (int kt = 0; kt < 4; ++kt)
; #pragma unroll
;                             for (int e = 0; e < 4; ++e) sc[u][kt][e] = fast_exp2(sc[u][kt][e]);
;     ...
; #pragma unroll
;                 for (int u = 0; u < 2; ++u) {
;                     const long pb0 = pack_fp8x8(sc[u][0][0], sc[u][0][1], sc[u][0][2], sc[u][0][3], sc[u][1][0], sc[u][1][1], sc[u][1][2], sc[u][1][3]);
;                     const long pb1 = pack_fp8x8(sc[u][2][0], sc[u][2][1], sc[u][2][2], sc[u][2][3], sc[u][3][0], sc[u][3][1], sc[u][3][2], sc[u][3][3]);
; #pragma unroll
.Lsel_fast:
	s_cmp_eq_u32 s44, 1
	s_cbranch_scc1 .Lfast_first
	s_cmp_ge_u32 s44, s41
	s_cbranch_scc1 .Lfast_pipe_last
	s_ashr_i32 s23, s22, 31
	s_lshl_b64 s[46:47], s[22:23], 12
	v_lshl_add_u64 v[234:235], v[150:151], 0, s[46:47]
	s_ashr_i32 s9, s8, 31
	s_lshl_b64 s[46:47], s[8:9], 12
	v_lshl_add_u64 v[236:237], v[150:151], 0, s[46:47]
	s_waitcnt vmcnt(15)
	v_mfma_f32_16x16x32_fp8_fp8 v[48:51], v[84:85], v[244:245], v[48:51]
	v_max3_f32 v1, v116, v117, v118
	v_max3_f32 v2, v119, v108, v109
	v_mfma_f32_16x16x32_fp8_fp8 v[52:55], v[242:243], v[244:245], v[52:55]
	v_max3_f32 v3, v110, v111, v100
	v_max3_f32 v120, v101, v102, v103
	s_waitcnt vmcnt(14)
	v_mfma_f32_16x16x32_fp8_fp8 v[44:47], v[80:81], v[244:245], v[44:47]
	v_max3_f32 v121, v112, v113, v114
	v_max3_f32 v122, v115, v104, v105
	s_waitcnt vmcnt(13)
	v_mfma_f32_16x16x32_fp8_fp8 v[40:43], v[76:77], v[244:245], v[40:43]
	v_max3_f32 v123, v106, v107, v96
	v_max3_f32 v1, v1, v97, v98
	s_waitcnt vmcnt(12)
	v_mfma_f32_16x16x32_fp8_fp8 v[24:27], v[72:73], v[244:245], v[24:27]
	v_max3_f32 v2, v2, v99, v92
	v_max3_f32 v3, v3, v93, v94
	v_mfma_f32_16x16x32_fp8_fp8 v[48:51], v[86:87], v[246:247], v[48:51]
	global_load_dwordx4 v[84:87], v[234:235], off
	v_max3_f32 v120, v120, v95, v88
	v_max3_f32 v121, v121, v89, v90
	v_mfma_f32_16x16x32_fp8_fp8 v[44:47], v[82:83], v[246:247], v[44:47]
	global_load_dwordx4 v[80:83], v[234:235], off offset:1024
	v_max3_f32 v122, v122, v91, v123
	v_max3_f32 v1, v1, v2, v3
	v_mfma_f32_16x16x32_fp8_fp8 v[40:43], v[78:79], v[246:247], v[40:43]
	global_load_dwordx4 v[76:79], v[234:235], off offset:2048
	v_max3_f32 v120, v120, v121, v122
	v_max_f32_e32 v1, v1, v120
	v_mfma_f32_16x16x32_fp8_fp8 v[24:27], v[74:75], v[246:247], v[24:27]
	global_load_dwordx4 v[72:75], v[234:235], off offset:3072
	v_mov_b32_e32 v2, v1
	v_mfma_f32_16x16x32_fp8_fp8 v[52:55], v[242:243], v[246:247], v[52:55]
	s_nop 1
	v_permlane16_swap_b32_e32 v1, v2
	v_max_f32_e32 v1, v1, v2
	v_mov_b32_e32 v2, v1
	s_nop 1
	v_permlane32_swap_b32_e32 v1, v2
	v_max_f32_e32 v1, v1, v2
	v_add_f32_e32 v180, 0xc0c00000, v1
	v_pk_add_f32 v[2:3], v[156:157], v[180:181]
	v_cmp_lg_f32_e32 vcc, s81, v1
	v_cmp_gt_f32_e64 s[8:9], v2, v3
	s_nop 0
	s_and_b64 s[6:7], s[8:9], s[4:5]
	s_andn2_b64 s[46:47], vcc, s[4:5]
	s_or_b64 s[6:7], s[6:7], s[46:47]
	s_cbranch_scc0 .Lpipe_exp_nl
	s_waitcnt vmcnt(15)
	v_mfma_f32_16x16x32_fp8_fp8 v[48:51], v[68:69], v[248:249], v[48:51]
	v_mfma_f32_16x16x32_fp8_fp8 v[52:55], v[242:243], v[248:249], v[52:55]
	s_waitcnt vmcnt(14)
	v_mfma_f32_16x16x32_fp8_fp8 v[44:47], v[64:65], v[248:249], v[44:47]
	s_waitcnt vmcnt(13)
	v_mfma_f32_16x16x32_fp8_fp8 v[40:43], v[60:61], v[248:249], v[40:43]
	s_waitcnt vmcnt(12)
	v_mfma_f32_16x16x32_fp8_fp8 v[24:27], v[56:57], v[248:249], v[24:27]
	v_mfma_f32_16x16x32_fp8_fp8 v[48:51], v[70:71], v[250:251], v[48:51]
	global_load_dwordx4 v[68:71], v[236:237], off
	v_mfma_f32_16x16x32_fp8_fp8 v[44:47], v[66:67], v[250:251], v[44:47]
	global_load_dwordx4 v[64:67], v[236:237], off offset:1024
	v_mfma_f32_16x16x32_fp8_fp8 v[40:43], v[62:63], v[250:251], v[40:43]
	global_load_dwordx4 v[60:63], v[236:237], off offset:2048
	v_mfma_f32_16x16x32_fp8_fp8 v[24:27], v[58:59], v[250:251], v[24:27]
	global_load_dwordx4 v[56:59], v[236:237], off offset:3072
	v_mfma_f32_16x16x32_fp8_fp8 v[52:55], v[242:243], v[250:251], v[52:55]
	s_nop 7
	s_nop 1
	v_cndmask_b32_e64 v1, v157, v2, s[6:7]
	v_sub_f32_e32 v3, v157, v1
	v_exp_f32_e32 v3, v3
	s_and_b64 vcc, s[4:5], s[8:9]
	v_sub_f32_e32 v120, v2, v156
	v_mov_b32_e32 v157, v1
	v_cndmask_b32_e32 v2, 1.0, v3, vcc
	v_pk_mul_f32 v[50:51], v[50:51], v[2:3] op_sel_hi:[1,0]
	v_pk_mul_f32 v[48:49], v[48:49], v[2:3] op_sel_hi:[1,0]
	v_pk_mul_f32 v[46:47], v[46:47], v[2:3] op_sel_hi:[1,0]
	v_pk_mul_f32 v[44:45], v[44:45], v[2:3] op_sel_hi:[1,0]
	v_pk_mul_f32 v[42:43], v[42:43], v[2:3] op_sel_hi:[1,0]
	v_pk_mul_f32 v[40:41], v[40:41], v[2:3] op_sel_hi:[1,0]
	v_pk_mul_f32 v[26:27], v[26:27], v[2:3] op_sel_hi:[1,0]
	v_pk_mul_f32 v[24:25], v[24:25], v[2:3] op_sel_hi:[1,0]
	v_pk_mul_f32 v[54:55], v[54:55], v[2:3] op_sel_hi:[1,0]
	v_pk_mul_f32 v[52:53], v[52:53], v[2:3] op_sel_hi:[1,0]
	v_cndmask_b32_e64 v3, 0, v120, s[6:7]
	v_sub_f32_e32 v116, v116, v3
	v_sub_f32_e32 v117, v117, v3
	v_sub_f32_e32 v118, v118, v3
	v_sub_f32_e32 v119, v119, v3
	v_sub_f32_e32 v108, v108, v3
	v_sub_f32_e32 v109, v109, v3
	v_sub_f32_e32 v110, v110, v3
	v_sub_f32_e32 v111, v111, v3
	v_sub_f32_e32 v96, v96, v3
	v_sub_f32_e32 v97, v97, v3
	v_sub_f32_e32 v98, v98, v3
	v_sub_f32_e32 v99, v99, v3
	v_sub_f32_e32 v100, v100, v3
	v_sub_f32_e32 v101, v101, v3
	v_sub_f32_e32 v102, v102, v3
	v_sub_f32_e32 v103, v103, v3
	v_sub_f32_e32 v112, v112, v3
	v_sub_f32_e32 v113, v113, v3
	v_sub_f32_e32 v114, v114, v3
	v_sub_f32_e32 v115, v115, v3
	v_sub_f32_e32 v104, v104, v3
	v_sub_f32_e32 v105, v105, v3
	v_sub_f32_e32 v106, v106, v3
	v_sub_f32_e32 v107, v107, v3
	v_sub_f32_e32 v92, v92, v3
	v_sub_f32_e32 v93, v93, v3
	v_sub_f32_e32 v94, v94, v3
	v_sub_f32_e32 v95, v95, v3
	v_sub_f32_e32 v88, v88, v3
	v_sub_f32_e32 v89, v89, v3
	v_sub_f32_e32 v90, v90, v3
	v_sub_f32_e32 v91, v91, v3
	s_branch .Lsel_exp_plain
; __device__ __forceinline__ float fast_exp2(float x) { return __builtin_amdgcn_exp2f(x); }
; __device__ __forceinline__ void nsa_unit(const Params& p, int bg, int jq, LAS unsigned char* lds, int wave, int lane, bool build_lut) {
;     ...
;                     for (int u = 0; u < 2; ++u) {
;                         float tt = fmaxf(fmaxf(fmaxf(sc[u][0][0], sc[u][0][1]), fmaxf(sc[u][0][2], sc[u][0][3])), fmaxf(fmaxf(sc[u][1][0], sc[u][1][1]), fmaxf(sc[u][1][2], sc[u][1][3])));
;                         tt = fmaxf(tt, fmaxf(fmaxf(fmaxf(sc[u][2][0], sc[u][2][1]), fmaxf(sc[u][2][2], sc[u][2][3])), fmaxf(fmaxf(sc[u][3][0], sc[u][3][1]), fmaxf(sc[u][3][2], sc[u][3][3]))));
;                         t = fmaxf(t, tt);
;                     }
;                     { auto t1 = __builtin_amdgcn_permlane16_swap(__float_as_uint(t), __float_as_uint(t), false, false); t = fmaxf(__uint_as_float(t1[0]), __uint_as_float(t1[1])); t = xhalf_max(t); }
;                     const float mxt = t - 6.0f + mref;
;                     const bool need = fresh ? (t > NEG_INF) : (mxt > m + 2.0f);
;                     if (__any(need)) {
;                         const float mnew = need ? mxt : m;
;                         const float delta = need ? (mnew - mref) : 0.f;
;                         const float alpha = (need && !fresh) ? fast_exp2(m - mnew) : 1.0f;
;                         lacc = lacc * alpha; m = mnew;
; #pragma unroll
;                         for (int dt = 0; dt < 4; ++dt) o[dt] = o[dt] * alpha;
; #pragma unroll
;                         for (int u = 0; u < 2; ++u)
; #pragma unroll
;                             for (int kt = 0; kt < 4; ++kt) sc[u][kt] = sc[u][kt] - delta;
;                     }
; #pragma unroll
;                     for (int u = 0; u < 2; ++u)
; #pragma unroll
;                         for (int kt = 0; kt < 4; ++kt)
; #pragma unroll
;                             for (int e = 0; e < 4; ++e) sc[u][kt][e] = fast_exp2(sc[u][kt][e]);
;     ...
;                 for (int u = 0; u < 2; ++u) {
;                     const long pb0 = pack_fp8x8(sc[u][0][0], sc[u][0][1], sc[u][0][2], sc[u][0][3], sc[u][1][0], sc[u][1][1], sc[u][1][2], sc[u][1][3]);
;                     const long pb1 = pack_fp8x8(sc[u][2][0], sc[u][2][1], sc[u][2][2], sc[u][2][3], sc[u][3][0], sc[u][3][1], sc[u][3][2], sc[u][3][3]);
; #pragma unroll
;                     for (int dt = 0; dt < 4; ++dt) {
.Lpipe_exp_nl:
	s_waitcnt vmcnt(15)
	v_mfma_f32_16x16x32_fp8_fp8 v[48:51], v[68:69], v[248:249], v[48:51]
	v_exp_f32_e32 v116, v116
	v_exp_f32_e32 v117, v117
	v_mfma_f32_16x16x32_fp8_fp8 v[52:55], v[242:243], v[248:249], v[52:55]
	v_exp_f32_e32 v118, v118
	v_exp_f32_e32 v119, v119
	s_waitcnt vmcnt(14)
	v_mfma_f32_16x16x32_fp8_fp8 v[44:47], v[64:65], v[248:249], v[44:47]
	v_exp_f32_e32 v108, v108
	v_exp_f32_e32 v109, v109
	s_waitcnt vmcnt(13)
	v_mfma_f32_16x16x32_fp8_fp8 v[40:43], v[60:61], v[248:249], v[40:43]
	v_exp_f32_e32 v110, v110
	v_exp_f32_e32 v111, v111
	s_waitcnt vmcnt(12)
	v_mfma_f32_16x16x32_fp8_fp8 v[24:27], v[56:57], v[248:249], v[24:27]
	v_exp_f32_e32 v96, v96
	v_exp_f32_e32 v97, v97
	v_mfma_f32_16x16x32_fp8_fp8 v[48:51], v[70:71], v[250:251], v[48:51]
	global_load_dwordx4 v[68:71], v[236:237], off
	v_exp_f32_e32 v98, v98
	v_exp_f32_e32 v99, v99
	v_mfma_f32_16x16x32_fp8_fp8 v[44:47], v[66:67], v[250:251], v[44:47]
	global_load_dwordx4 v[64:67], v[236:237], off offset:1024
	v_exp_f32_e32 v100, v100
	v_exp_f32_e32 v101, v101
	v_mfma_f32_16x16x32_fp8_fp8 v[40:43], v[62:63], v[250:251], v[40:43]
	global_load_dwordx4 v[60:63], v[236:237], off offset:2048
	v_exp_f32_e32 v102, v102
	v_exp_f32_e32 v103, v103
	v_mfma_f32_16x16x32_fp8_fp8 v[24:27], v[58:59], v[250:251], v[24:27]
	global_load_dwordx4 v[56:59], v[236:237], off offset:3072
	v_exp_f32_e32 v112, v112
	v_exp_f32_e32 v113, v113
	v_mfma_f32_16x16x32_fp8_fp8 v[52:55], v[242:243], v[250:251], v[52:55]
	v_exp_f32_e32 v114, v114
	v_exp_f32_e32 v115, v115
	v_exp_f32_e32 v104, v104
	v_exp_f32_e32 v105, v105
	v_exp_f32_e32 v106, v106
	v_exp_f32_e32 v107, v107
	v_exp_f32_e32 v92, v92
	v_exp_f32_e32 v93, v93
	v_exp_f32_e32 v94, v94
	v_exp_f32_e32 v95, v95
	v_exp_f32_e32 v88, v88
	v_exp_f32_e32 v89, v89
	v_exp_f32_e32 v90, v90
	v_exp_f32_e32 v91, v91
	v_cvt_pk_fp8_f32 v244, v116, v117
	v_cvt_pk_fp8_f32 v245, v108, v109
	v_cvt_pk_fp8_f32 v246, v96, v97
	v_cvt_pk_fp8_f32 v247, v100, v101
	v_cvt_pk_fp8_f32 v244, v118, v119 op_sel:[0,0,1]
	v_cvt_pk_fp8_f32 v245, v110, v111 op_sel:[0,0,1]
	v_cvt_pk_fp8_f32 v246, v98, v99 op_sel:[0,0,1]
	v_cvt_pk_fp8_f32 v247, v102, v103 op_sel:[0,0,1]
	v_cvt_pk_fp8_f32 v248, v112, v113
	v_cvt_pk_fp8_f32 v249, v104, v105
	v_cvt_pk_fp8_f32 v250, v92, v93
	v_cvt_pk_fp8_f32 v251, v88, v89
	v_cvt_pk_fp8_f32 v248, v114, v115 op_sel:[0,0,1]
	v_cvt_pk_fp8_f32 v249, v106, v107 op_sel:[0,0,1]
	v_cvt_pk_fp8_f32 v250, v94, v95 op_sel:[0,0,1]
	v_cvt_pk_fp8_f32 v251, v90, v91 op_sel:[0,0,1]
	s_branch .Lsel_next
.Lfast_pipe_last:
	s_ashr_i32 s23, s22, 31
	s_lshl_b64 s[46:47], s[22:23], 12
	v_lshl_add_u64 v[234:235], v[150:151], 0, s[46:47]
	s_ashr_i32 s9, s8, 31
	s_lshl_b64 s[46:47], s[8:9], 12
	v_lshl_add_u64 v[236:237], v[150:151], 0, s[46:47]
	s_waitcnt vmcnt(7)
	v_mfma_f32_16x16x32_fp8_fp8 v[48:51], v[84:85], v[244:245], v[48:51]
	v_max3_f32 v1, v116, v117, v118
	v_max3_f32 v2, v119, v108, v109
	v_mfma_f32_16x16x32_fp8_fp8 v[52:55], v[242:243], v[244:245], v[52:55]
	v_max3_f32 v3, v110, v111, v100
	v_max3_f32 v120, v101, v102, v103
	s_waitcnt vmcnt(6)
	v_mfma_f32_16x16x32_fp8_fp8 v[44:47], v[80:81], v[244:245], v[44:47]
	v_max3_f32 v121, v112, v113, v114
	v_max3_f32 v122, v115, v104, v105
	s_waitcnt vmcnt(5)
	v_mfma_f32_16x16x32_fp8_fp8 v[40:43], v[76:77], v[244:245], v[40:43]
	v_max3_f32 v123, v106, v107, v96
	v_max3_f32 v1, v1, v97, v98
	s_waitcnt vmcnt(4)
	v_mfma_f32_16x16x32_fp8_fp8 v[24:27], v[72:73], v[244:245], v[24:27]
	v_max3_f32 v2, v2, v99, v92
	v_max3_f32 v3, v3, v93, v94
	v_mfma_f32_16x16x32_fp8_fp8 v[48:51], v[86:87], v[246:247], v[48:51]
	global_load_dwordx4 v[84:87], v[234:235], off
	v_max3_f32 v120, v120, v95, v88
	v_max3_f32 v121, v121, v89, v90
	v_mfma_f32_16x16x32_fp8_fp8 v[44:47], v[82:83], v[246:247], v[44:47]
	global_load_dwordx4 v[80:83], v[234:235], off offset:1024
	v_max3_f32 v122, v122, v91, v123
	v_max3_f32 v1, v1, v2, v3
	v_mfma_f32_16x16x32_fp8_fp8 v[40:43], v[78:79], v[246:247], v[40:43]
	global_load_dwordx4 v[76:79], v[234:235], off offset:2048
	v_max3_f32 v120, v120, v121, v122
	v_max_f32_e32 v1, v1, v120
	v_mfma_f32_16x16x32_fp8_fp8 v[24:27], v[74:75], v[246:247], v[24:27]
	global_load_dwordx4 v[72:75], v[234:235], off offset:3072
	v_mov_b32_e32 v2, v1
	v_mfma_f32_16x16x32_fp8_fp8 v[52:55], v[242:243], v[246:247], v[52:55]
	s_nop 1
	v_permlane16_swap_b32_e32 v1, v2
	v_max_f32_e32 v1, v1, v2
	v_mov_b32_e32 v2, v1
	s_nop 1
	v_permlane32_swap_b32_e32 v1, v2
	v_max_f32_e32 v1, v1, v2
	v_add_f32_e32 v180, 0xc0c00000, v1
	v_pk_add_f32 v[2:3], v[156:157], v[180:181]
	v_cmp_lg_f32_e32 vcc, s81, v1
	v_cmp_gt_f32_e64 s[8:9], v2, v3
	s_nop 0
	s_and_b64 s[6:7], s[8:9], s[4:5]
	s_andn2_b64 s[46:47], vcc, s[4:5]
	s_or_b64 s[6:7], s[6:7], s[46:47]
	s_cbranch_scc0 .Lpipe_exp_la
; __device__ __forceinline__ float fast_exp2(float x) { return __builtin_amdgcn_exp2f(x); }
; __device__ __forceinline__ void nsa_unit(const Params& p, int bg, int jq, LAS unsigned char* lds, int wave, int lane, bool build_lut) {
;     ...
;                     if (__any(need)) {
;                         const float mnew = need ? mxt : m;
;                         const float delta = need ? (mnew - mref) : 0.f;
;                         const float alpha = (need && !fresh) ? fast_exp2(m - mnew) : 1.0f;
;                         lacc = lacc * alpha; m = mnew;
; #pragma unroll
;                         for (int dt = 0; dt < 4; ++dt) o[dt] = o[dt] * alpha;
; #pragma unroll
;                         for (int u = 0; u < 2; ++u)
; #pragma unroll
;                             for (int kt = 0; kt < 4; ++kt) sc[u][kt] = sc[u][kt] - delta;
;                     }
; #pragma unroll
;                     for (int u = 0; u < 2; ++u)
; #pragma unroll
;                         for (int kt = 0; kt < 4; ++kt)
; #pragma unroll
;                             for (int e = 0; e < 4; ++e) sc[u][kt][e] = fast_exp2(sc[u][kt][e]);
;     ...
;                 for (int u = 0; u < 2; ++u) {
;                     const long pb0 = pack_fp8x8(sc[u][0][0], sc[u][0][1], sc[u][0][2], sc[u][0][3], sc[u][1][0], sc[u][1][1], sc[u][1][2], sc[u][1][3]);
;                     const long pb1 = pack_fp8x8(sc[u][2][0], sc[u][2][1], sc[u][2][2], sc[u][2][3], sc[u][3][0], sc[u][3][1], sc[u][3][2], sc[u][3][3]);
; #pragma unroll
;                     for (int dt = 0; dt < 4; ++dt) {
;                         o[dt] = __builtin_amdgcn_mfma_f32_16x16x32_fp8_fp8(v8[u][2 * dt], pb0, o[dt], 0, 0, 0);
;                         o[dt] = __builtin_amdgcn_mfma_f32_16x16x32_fp8_fp8(v8[u][2 * dt + 1], pb1, o[dt], 0, 0, 0);
;                     }
;                     lacc = __builtin_amdgcn_mfma_f32_16x16x32_fp8_fp8(ones8, pb0, lacc, 0, 0, 0);
;                     lacc = __builtin_amdgcn_mfma_f32_16x16x32_fp8_fp8(ones8, pb1, lacc, 0, 0, 0);
;                 }
	s_waitcnt vmcnt(7)
	v_mfma_f32_16x16x32_fp8_fp8 v[48:51], v[68:69], v[248:249], v[48:51]
	v_mfma_f32_16x16x32_fp8_fp8 v[52:55], v[242:243], v[248:249], v[52:55]
	s_waitcnt vmcnt(6)
	v_mfma_f32_16x16x32_fp8_fp8 v[44:47], v[64:65], v[248:249], v[44:47]
	s_waitcnt vmcnt(5)
	v_mfma_f32_16x16x32_fp8_fp8 v[40:43], v[60:61], v[248:249], v[40:43]
	s_waitcnt vmcnt(4)
	v_mfma_f32_16x16x32_fp8_fp8 v[24:27], v[56:57], v[248:249], v[24:27]
	v_mfma_f32_16x16x32_fp8_fp8 v[48:51], v[70:71], v[250:251], v[48:51]
	global_load_dwordx4 v[68:71], v[236:237], off
	v_mfma_f32_16x16x32_fp8_fp8 v[44:47], v[66:67], v[250:251], v[44:47]
	global_load_dwordx4 v[64:67], v[236:237], off offset:1024
	v_mfma_f32_16x16x32_fp8_fp8 v[40:43], v[62:63], v[250:251], v[40:43]
	global_load_dwordx4 v[60:63], v[236:237], off offset:2048
	v_mfma_f32_16x16x32_fp8_fp8 v[24:27], v[58:59], v[250:251], v[24:27]
	global_load_dwordx4 v[56:59], v[236:237], off offset:3072
	v_mfma_f32_16x16x32_fp8_fp8 v[52:55], v[242:243], v[250:251], v[52:55]
	s_nop 7
	s_nop 1
	v_cndmask_b32_e64 v1, v157, v2, s[6:7]
	v_sub_f32_e32 v3, v157, v1
	v_exp_f32_e32 v3, v3
	s_and_b64 vcc, s[4:5], s[8:9]
	v_sub_f32_e32 v120, v2, v156
	v_mov_b32_e32 v157, v1
	v_cndmask_b32_e32 v2, 1.0, v3, vcc
	v_pk_mul_f32 v[50:51], v[50:51], v[2:3] op_sel_hi:[1,0]
	v_pk_mul_f32 v[48:49], v[48:49], v[2:3] op_sel_hi:[1,0]
	v_pk_mul_f32 v[46:47], v[46:47], v[2:3] op_sel_hi:[1,0]
	v_pk_mul_f32 v[44:45], v[44:45], v[2:3] op_sel_hi:[1,0]
	v_pk_mul_f32 v[42:43], v[42:43], v[2:3] op_sel_hi:[1,0]
	v_pk_mul_f32 v[40:41], v[40:41], v[2:3] op_sel_hi:[1,0]
	v_pk_mul_f32 v[26:27], v[26:27], v[2:3] op_sel_hi:[1,0]
	v_pk_mul_f32 v[24:25], v[24:25], v[2:3] op_sel_hi:[1,0]
	v_pk_mul_f32 v[54:55], v[54:55], v[2:3] op_sel_hi:[1,0]
	v_pk_mul_f32 v[52:53], v[52:53], v[2:3] op_sel_hi:[1,0]
	v_cndmask_b32_e64 v3, 0, v120, s[6:7]
	v_sub_f32_e32 v116, v116, v3
	v_sub_f32_e32 v117, v117, v3
	v_sub_f32_e32 v118, v118, v3
	v_sub_f32_e32 v119, v119, v3
	v_sub_f32_e32 v108, v108, v3
	v_sub_f32_e32 v109, v109, v3
	v_sub_f32_e32 v110, v110, v3
	v_sub_f32_e32 v111, v111, v3
	v_sub_f32_e32 v96, v96, v3
	v_sub_f32_e32 v97, v97, v3
	v_sub_f32_e32 v98, v98, v3
	v_sub_f32_e32 v99, v99, v3
	v_sub_f32_e32 v100, v100, v3
	v_sub_f32_e32 v101, v101, v3
	v_sub_f32_e32 v102, v102, v3
	v_sub_f32_e32 v103, v103, v3
	v_sub_f32_e32 v112, v112, v3
	v_sub_f32_e32 v113, v113, v3
	v_sub_f32_e32 v114, v114, v3
	v_sub_f32_e32 v115, v115, v3
	v_sub_f32_e32 v104, v104, v3
	v_sub_f32_e32 v105, v105, v3
	v_sub_f32_e32 v106, v106, v3
	v_sub_f32_e32 v107, v107, v3
	v_sub_f32_e32 v92, v92, v3
	v_sub_f32_e32 v93, v93, v3
	v_sub_f32_e32 v94, v94, v3
	v_sub_f32_e32 v95, v95, v3
	v_sub_f32_e32 v88, v88, v3
	v_sub_f32_e32 v89, v89, v3
	v_sub_f32_e32 v90, v90, v3
	v_sub_f32_e32 v91, v91, v3
	s_branch .Lsel_exp_plain
.Lpipe_exp_la:
	s_waitcnt vmcnt(7)
	v_mfma_f32_16x16x32_fp8_fp8 v[48:51], v[68:69], v[248:249], v[48:51]
	v_exp_f32_e32 v116, v116
	v_exp_f32_e32 v117, v117
	v_mfma_f32_16x16x32_fp8_fp8 v[52:55], v[242:243], v[248:249], v[52:55]
	v_exp_f32_e32 v118, v118
	v_exp_f32_e32 v119, v119
	s_waitcnt vmcnt(6)
	v_mfma_f32_16x16x32_fp8_fp8 v[44:47], v[64:65], v[248:249], v[44:47]
	v_exp_f32_e32 v108, v108
	v_exp_f32_e32 v109, v109
	s_waitcnt vmcnt(5)
	v_mfma_f32_16x16x32_fp8_fp8 v[40:43], v[60:61], v[248:249], v[40:43]
	v_exp_f32_e32 v110, v110
	v_exp_f32_e32 v111, v111
	s_waitcnt vmcnt(4)
	v_mfma_f32_16x16x32_fp8_fp8 v[24:27], v[56:57], v[248:249], v[24:27]
	v_exp_f32_e32 v96, v96
	v_exp_f32_e32 v97, v97
	v_mfma_f32_16x16x32_fp8_fp8 v[48:51], v[70:71], v[250:251], v[48:51]
	global_load_dwordx4 v[68:71], v[236:237], off
	v_exp_f32_e32 v98, v98
	v_exp_f32_e32 v99, v99
	v_mfma_f32_16x16x32_fp8_fp8 v[44:47], v[66:67], v[250:251], v[44:47]
	global_load_dwordx4 v[64:67], v[236:237], off offset:1024
	v_exp_f32_e32 v100, v100
	v_exp_f32_e32 v101, v101
	v_mfma_f32_16x16x32_fp8_fp8 v[40:43], v[62:63], v[250:251], v[40:43]
	global_load_dwordx4 v[60:63], v[236:237], off offset:2048
	v_exp_f32_e32 v102, v102
	v_exp_f32_e32 v103, v103
	v_mfma_f32_16x16x32_fp8_fp8 v[24:27], v[58:59], v[250:251], v[24:27]
	global_load_dwordx4 v[56:59], v[236:237], off offset:3072
	v_exp_f32_e32 v112, v112
	v_exp_f32_e32 v113, v113
	v_mfma_f32_16x16x32_fp8_fp8 v[52:55], v[242:243], v[250:251], v[52:55]
	v_exp_f32_e32 v114, v114
	v_exp_f32_e32 v115, v115
	v_exp_f32_e32 v104, v104
	v_exp_f32_e32 v105, v105
	v_exp_f32_e32 v106, v106
	v_exp_f32_e32 v107, v107
	v_exp_f32_e32 v92, v92
	v_exp_f32_e32 v93, v93
	v_exp_f32_e32 v94, v94
	v_exp_f32_e32 v95, v95
	v_exp_f32_e32 v88, v88
	v_exp_f32_e32 v89, v89
	v_exp_f32_e32 v90, v90
	v_exp_f32_e32 v91, v91
	v_cvt_pk_fp8_f32 v244, v116, v117
	v_cvt_pk_fp8_f32 v245, v108, v109
	v_cvt_pk_fp8_f32 v246, v96, v97
	v_cvt_pk_fp8_f32 v247, v100, v101
	v_cvt_pk_fp8_f32 v244, v118, v119 op_sel:[0,0,1]
	v_cvt_pk_fp8_f32 v245, v110, v111 op_sel:[0,0,1]
	v_cvt_pk_fp8_f32 v246, v98, v99 op_sel:[0,0,1]
	v_cvt_pk_fp8_f32 v247, v102, v103 op_sel:[0,0,1]
	v_cvt_pk_fp8_f32 v248, v112, v113
	v_cvt_pk_fp8_f32 v249, v104, v105
	v_cvt_pk_fp8_f32 v250, v92, v93
	v_cvt_pk_fp8_f32 v251, v88, v89
	v_cvt_pk_fp8_f32 v248, v114, v115 op_sel:[0,0,1]
	v_cvt_pk_fp8_f32 v249, v106, v107 op_sel:[0,0,1]
	v_cvt_pk_fp8_f32 v250, v94, v95 op_sel:[0,0,1]
	v_cvt_pk_fp8_f32 v251, v90, v91 op_sel:[0,0,1]
	s_branch .Lsel_next
; __device__ __forceinline__ void nsa_unit(const Params& p, int bg, int jq, LAS unsigned char* lds, int wave, int lane, bool build_lut) {
;     ...
;                 if (fast) {
;                     float t = NEG_INF;
; #pragma unroll
;                     for (int u = 0; u < 2; ++u) {
;                         float tt = fmaxf(fmaxf(fmaxf(sc[u][0][0], sc[u][0][1]), fmaxf(sc[u][0][2], sc[u][0][3])), fmaxf(fmaxf(sc[u][1][0], sc[u][1][1]), fmaxf(sc[u][1][2], sc[u][1][3])));
;                         tt = fmaxf(tt, fmaxf(fmaxf(fmaxf(sc[u][2][0], sc[u][2][1]), fmaxf(sc[u][2][2], sc[u][2][3])), fmaxf(fmaxf(sc[u][3][0], sc[u][3][1]), fmaxf(sc[u][3][2], sc[u][3][3]))));
;                         t = fmaxf(t, tt);
;                     }
;                     { auto t1 = __builtin_amdgcn_permlane16_swap(__float_as_uint(t), __float_as_uint(t), false, false); t = fmaxf(__uint_as_float(t1[0]), __uint_as_float(t1[1])); t = xhalf_max(t); }
;                     const float mxt = t - 6.0f + mref;
;                     const bool need = fresh ? (t > NEG_INF) : (mxt > m + 2.0f);
;                     if (__any(need)) {
;                         const float mnew = need ? mxt : m;
;                         const float delta = need ? (mnew - mref) : 0.f;
;                         const float alpha = (need && !fresh) ? fast_exp2(m - mnew) : 1.0f;
;                         lacc = lacc * alpha; m = mnew;
; #pragma unroll
;                         for (int dt = 0; dt < 4; ++dt) o[dt] = o[dt] * alpha;
; #pragma unroll
;                         for (int u = 0; u < 2; ++u)
; #pragma unroll
;                             for (int kt = 0; kt < 4; ++kt) sc[u][kt] = sc[u][kt] - delta;
;                     }
; #pragma unroll
;                     for (int u = 0; u < 2; ++u)
; #pragma unroll
;                         for (int kt = 0; kt < 4; ++kt)
; #pragma unroll
;                             for (int e = 0; e < 4; ++e) sc[u][kt][e] = fast_exp2(sc[u][kt][e]);
;     ...
;                 for (int u = 0; u < 2; ++u) {
;                     const long pb0 = pack_fp8x8(sc[u][0][0], sc[u][0][1], sc[u][0][2], sc[u][0][3], sc[u][1][0], sc[u][1][1], sc[u][1][2], sc[u][1][3]);
;                     const long pb1 = pack_fp8x8(sc[u][2][0], sc[u][2][1], sc[u][2][2], sc[u][2][3], sc[u][3][0], sc[u][3][1], sc[u][3][2], sc[u][3][3]);
; #pragma unroll
;                     for (int dt = 0; dt < 4; ++dt) {
.Lfast_first:
	s_ashr_i32 s23, s22, 31
	s_lshl_b64 s[46:47], s[22:23], 12
	v_lshl_add_u64 v[234:235], v[150:151], 0, s[46:47]
	s_ashr_i32 s9, s8, 31
	s_lshl_b64 s[46:47], s[8:9], 12
	v_lshl_add_u64 v[236:237], v[150:151], 0, s[46:47]
	global_load_dwordx4 v[84:87], v[234:235], off
	global_load_dwordx4 v[80:83], v[234:235], off offset:1024
	global_load_dwordx4 v[76:79], v[234:235], off offset:2048
	global_load_dwordx4 v[72:75], v[234:235], off offset:3072
	global_load_dwordx4 v[68:71], v[236:237], off
	global_load_dwordx4 v[64:67], v[236:237], off offset:1024
	global_load_dwordx4 v[60:63], v[236:237], off offset:2048
	global_load_dwordx4 v[56:59], v[236:237], off offset:3072
	v_max3_f32 v1, v116, v117, v118
	v_max3_f32 v2, v119, v108, v109
	v_max3_f32 v3, v110, v111, v100
	v_max3_f32 v120, v101, v102, v103
	v_max3_f32 v121, v112, v113, v114
	v_max3_f32 v122, v115, v104, v105
	v_max3_f32 v123, v106, v107, v96
	v_max3_f32 v1, v1, v97, v98
	v_max3_f32 v2, v2, v99, v92
	v_max3_f32 v3, v3, v93, v94
	v_max3_f32 v120, v120, v95, v88
	v_max3_f32 v121, v121, v89, v90
	v_max3_f32 v122, v122, v91, v123
	v_max3_f32 v1, v1, v2, v3
	v_max3_f32 v120, v120, v121, v122
	v_max_f32_e32 v1, v1, v120
	v_mov_b32_e32 v2, v1
	s_nop 1
	v_permlane16_swap_b32_e32 v1, v2
	v_max_f32_e32 v1, v1, v2
	v_mov_b32_e32 v2, v1
	s_nop 1
	v_permlane32_swap_b32_e32 v1, v2
	v_max_f32_e32 v1, v1, v2
	v_add_f32_e32 v180, 0xc0c00000, v1
	v_pk_add_f32 v[2:3], v[156:157], v[180:181]
	v_cmp_lg_f32_e32 vcc, s81, v1
	v_cmp_gt_f32_e64 s[8:9], v2, v3
	s_nop 0
	s_and_b64 s[6:7], s[8:9], s[4:5]
	s_andn2_b64 s[46:47], vcc, s[4:5]
	s_or_b64 s[6:7], s[6:7], s[46:47]
	s_cbranch_scc0 .Lsel_exp_plain
	v_cndmask_b32_e64 v1, v157, v2, s[6:7]
	v_sub_f32_e32 v3, v157, v1
	v_exp_f32_e32 v3, v3
	s_and_b64 vcc, s[4:5], s[8:9]
	v_sub_f32_e32 v120, v2, v156
	v_mov_b32_e32 v157, v1
	v_cndmask_b32_e32 v2, 1.0, v3, vcc
	v_pk_mul_f32 v[50:51], v[50:51], v[2:3] op_sel_hi:[1,0]
	v_pk_mul_f32 v[48:49], v[48:49], v[2:3] op_sel_hi:[1,0]
	v_pk_mul_f32 v[46:47], v[46:47], v[2:3] op_sel_hi:[1,0]
	v_pk_mul_f32 v[44:45], v[44:45], v[2:3] op_sel_hi:[1,0]
	v_pk_mul_f32 v[42:43], v[42:43], v[2:3] op_sel_hi:[1,0]
	v_pk_mul_f32 v[40:41], v[40:41], v[2:3] op_sel_hi:[1,0]
	v_pk_mul_f32 v[26:27], v[26:27], v[2:3] op_sel_hi:[1,0]
	v_pk_mul_f32 v[24:25], v[24:25], v[2:3] op_sel_hi:[1,0]
	v_pk_mul_f32 v[54:55], v[54:55], v[2:3] op_sel_hi:[1,0]
	v_pk_mul_f32 v[52:53], v[52:53], v[2:3] op_sel_hi:[1,0]
	v_cndmask_b32_e64 v3, 0, v120, s[6:7]
	v_sub_f32_e32 v116, v116, v3
	v_sub_f32_e32 v117, v117, v3
	v_sub_f32_e32 v118, v118, v3
	v_sub_f32_e32 v119, v119, v3
	v_sub_f32_e32 v108, v108, v3
	v_sub_f32_e32 v109, v109, v3
	v_sub_f32_e32 v110, v110, v3
	v_sub_f32_e32 v111, v111, v3
	v_sub_f32_e32 v96, v96, v3
	v_sub_f32_e32 v97, v97, v3
	v_sub_f32_e32 v98, v98, v3
	v_sub_f32_e32 v99, v99, v3
	v_sub_f32_e32 v100, v100, v3
	v_sub_f32_e32 v101, v101, v3
	v_sub_f32_e32 v102, v102, v3
	v_sub_f32_e32 v103, v103, v3
	v_sub_f32_e32 v112, v112, v3
	v_sub_f32_e32 v113, v113, v3
	v_sub_f32_e32 v114, v114, v3
	v_sub_f32_e32 v115, v115, v3
	v_sub_f32_e32 v104, v104, v3
	v_sub_f32_e32 v105, v105, v3
	v_sub_f32_e32 v106, v106, v3
	v_sub_f32_e32 v107, v107, v3
	v_sub_f32_e32 v92, v92, v3
	v_sub_f32_e32 v93, v93, v3
	v_sub_f32_e32 v94, v94, v3
	v_sub_f32_e32 v95, v95, v3
	v_sub_f32_e32 v88, v88, v3
	v_sub_f32_e32 v89, v89, v3
	v_sub_f32_e32 v90, v90, v3
	v_sub_f32_e32 v91, v91, v3
.Lsel_exp_plain:
	v_exp_f32_e32 v116, v116
	v_exp_f32_e32 v117, v117
	v_exp_f32_e32 v118, v118
	v_exp_f32_e32 v119, v119
	v_exp_f32_e32 v108, v108
	v_exp_f32_e32 v109, v109
	v_exp_f32_e32 v110, v110
	v_exp_f32_e32 v111, v111
	v_exp_f32_e32 v96, v96
	v_exp_f32_e32 v97, v97
	v_exp_f32_e32 v98, v98
	v_exp_f32_e32 v99, v99
	v_exp_f32_e32 v100, v100
	v_exp_f32_e32 v101, v101
	v_exp_f32_e32 v102, v102
	v_exp_f32_e32 v103, v103
	v_exp_f32_e32 v112, v112
	v_exp_f32_e32 v113, v113
	v_exp_f32_e32 v114, v114
	v_exp_f32_e32 v115, v115
	v_exp_f32_e32 v104, v104
	v_exp_f32_e32 v105, v105
	v_exp_f32_e32 v106, v106
	v_exp_f32_e32 v107, v107
	v_exp_f32_e32 v92, v92
	v_exp_f32_e32 v93, v93
	v_exp_f32_e32 v94, v94
	v_exp_f32_e32 v95, v95
	v_exp_f32_e32 v88, v88
	v_exp_f32_e32 v89, v89
	v_exp_f32_e32 v90, v90
	v_exp_f32_e32 v91, v91
	v_cvt_pk_fp8_f32 v244, v116, v117
	v_cvt_pk_fp8_f32 v245, v108, v109
	v_cvt_pk_fp8_f32 v246, v96, v97
	v_cvt_pk_fp8_f32 v247, v100, v101
	v_cvt_pk_fp8_f32 v244, v118, v119 op_sel:[0,0,1]
	v_cvt_pk_fp8_f32 v245, v110, v111 op_sel:[0,0,1]
	v_cvt_pk_fp8_f32 v246, v98, v99 op_sel:[0,0,1]
	v_cvt_pk_fp8_f32 v247, v102, v103 op_sel:[0,0,1]
	v_cvt_pk_fp8_f32 v248, v112, v113
	v_cvt_pk_fp8_f32 v249, v104, v105
	v_cvt_pk_fp8_f32 v250, v92, v93
	v_cvt_pk_fp8_f32 v251, v88, v89
	v_cvt_pk_fp8_f32 v248, v114, v115 op_sel:[0,0,1]
	v_cvt_pk_fp8_f32 v249, v106, v107 op_sel:[0,0,1]
	v_cvt_pk_fp8_f32 v250, v94, v95 op_sel:[0,0,1]
	v_cvt_pk_fp8_f32 v251, v90, v91 op_sel:[0,0,1]
.Lsel_next:
	s_add_i32 s43, s43, 8
	s_add_i32 s40, s40, 2
	s_cmp_ge_u32 s44, s41
	s_cbranch_scc1 .Lsel_exit
	s_mov_b32 s8, s18
	s_mov_b32 s22, s16
	s_branch .LBB0_1200
.Lsel_exit:
	s_waitcnt vmcnt(7)
	v_mfma_f32_16x16x32_fp8_fp8 v[48:51], v[84:85], v[244:245], v[48:51]
	v_mfma_f32_16x16x32_fp8_fp8 v[52:55], v[242:243], v[244:245], v[52:55]
	s_waitcnt vmcnt(6)
	v_mfma_f32_16x16x32_fp8_fp8 v[44:47], v[80:81], v[244:245], v[44:47]
	s_waitcnt vmcnt(5)
	v_mfma_f32_16x16x32_fp8_fp8 v[40:43], v[76:77], v[244:245], v[40:43]
	s_waitcnt vmcnt(4)
	v_mfma_f32_16x16x32_fp8_fp8 v[24:27], v[72:73], v[244:245], v[24:27]
	v_mfma_f32_16x16x32_fp8_fp8 v[48:51], v[86:87], v[246:247], v[48:51]
	v_mfma_f32_16x16x32_fp8_fp8 v[44:47], v[82:83], v[246:247], v[44:47]
	v_mfma_f32_16x16x32_fp8_fp8 v[40:43], v[78:79], v[246:247], v[40:43]
	v_mfma_f32_16x16x32_fp8_fp8 v[24:27], v[74:75], v[246:247], v[24:27]
	v_mfma_f32_16x16x32_fp8_fp8 v[52:55], v[242:243], v[246:247], v[52:55]
	s_waitcnt vmcnt(3)
	v_mfma_f32_16x16x32_fp8_fp8 v[48:51], v[68:69], v[248:249], v[48:51]
	v_mfma_f32_16x16x32_fp8_fp8 v[52:55], v[242:243], v[248:249], v[52:55]
	s_waitcnt vmcnt(2)
	v_mfma_f32_16x16x32_fp8_fp8 v[44:47], v[64:65], v[248:249], v[44:47]
	s_waitcnt vmcnt(1)
	v_mfma_f32_16x16x32_fp8_fp8 v[40:43], v[60:61], v[248:249], v[40:43]
	s_waitcnt vmcnt(0)
	v_mfma_f32_16x16x32_fp8_fp8 v[24:27], v[56:57], v[248:249], v[24:27]
	v_mfma_f32_16x16x32_fp8_fp8 v[48:51], v[70:71], v[250:251], v[48:51]
	v_mfma_f32_16x16x32_fp8_fp8 v[44:47], v[66:67], v[250:251], v[44:47]
	v_mfma_f32_16x16x32_fp8_fp8 v[40:43], v[62:63], v[250:251], v[40:43]
	v_mfma_f32_16x16x32_fp8_fp8 v[24:27], v[58:59], v[250:251], v[24:27]
	v_mfma_f32_16x16x32_fp8_fp8 v[52:55], v[242:243], v[250:251], v[52:55]
	s_branch .LBB0_1278
